# P0 rope loop: pos loads of the first two iterations issued before the weight-transpose loop (no per-iteration load wait)
# baseline (speedup 1.0000x reference)
.LBB0_60:
	s_add_u32 s6, s30, 0x3900000
	s_addc_u32 s7, s31, 0
	s_add_u32 s12, s30, 0x3780000
	s_addc_u32 s13, s31, 0
	s_add_u32 s14, s30, 0x3a00000
	s_addc_u32 s15, s31, 0
	v_add_u32_e32 v29, 0x100, v16
	v_add_u32_e32 v21, 0x200, v16
	v_add_u32_e32 v25, 0x300, v16
	v_lshlrev_b32_e32 v27, 3, v16
	s_add_u32 s16, s30, 0x2000000
	v_and_b32_e32 v20, 60, v17
	v_ashrrev_i32_e32 v17, 4, v16
	v_ashrrev_i32_e32 v19, 4, v29
	v_ashrrev_i32_e32 v21, 4, v21
	v_ashrrev_i32_e32 v25, 4, v25
	v_and_b32_e32 v27, 56, v27
	s_movk_i32 s3, 0x104
	s_addc_u32 s17, s31, 0
	s_add_i32 s4, s66, s34
	v_lshl_add_u32 v22, v20, 2, 0
	v_mad_u32_u24 v33, v27, s3, 0
	v_ashrrev_i32_e32 v30, 3, v16
	v_mul_lo_u32 v34, v17, s3
	v_mul_lo_u32 v35, v19, s3
	v_mul_lo_u32 v36, v21, s3
	v_mul_lo_u32 v37, v25, s3
	v_ashrrev_i32_e32 v32, 3, v29
	s_lshl_b32 s3, s4, 1
	s_add_i32 s37, s4, 0xfffff040
	v_mov_b32_e32 v23, 0
	v_lshl_add_u32 v31, v30, 2, v33
	v_lshl_add_u32 v33, v32, 2, v33
	s_add_i32 s3, s3, 0x7fffdf00
	s_lshl_b32 s9, s34, 1
	s_lshl_b32 s33, s4, 6
	s_lshl_b32 s36, s34, 6
	s_lshl_b32 s38, s37, 6
	v_add_u32_e32 v34, v22, v34
	v_add_u32_e32 v35, v22, v35
	v_add_u32_e32 v36, v22, v36
	v_add_u32_e32 v37, v22, v37
	s_mov_b32 s39, s66
	s_mov_b64 s[18:19], s[10:11]
	s_mov_b32 s40, s1
	s_mov_b32 s41, s2
	v_readlane_b32 s98, v255, 5
	v_readlane_b32 s99, v255, 6
	s_lshl_b32 s100, s34, 8
	v_lshl_add_u32 v252, s66, 8, v16
	v_add_u32_e32 v253, s100, v252
	v_min_i32_e32 v252, 0x3ffff, v252
	v_min_i32_e32 v253, 0x3ffff, v253
	v_ashrrev_i32_e32 v252, 5, v252
	v_ashrrev_i32_e32 v253, 5, v253
	v_lshlrev_b32_e32 v252, 2, v252
	v_lshlrev_b32_e32 v253, 2, v253
	global_load_dword v252, v252, s[98:99]
	global_load_dword v253, v253, s[98:99]
	s_branch .LBB0_63

.LBB0_103:
	s_mov_b32 s98, 0
	s_waitcnt vmcnt(0)
	v_lshl_add_u32 v0, s66, 8, v16
	s_mov_b32 s1, 0x40000
	v_cmp_gt_i32_e32 vcc, s1, v0
	s_and_saveexec_b64 s[4:5], vcc
	v_readlane_b32 s8, v255, 3
	v_readlane_b32 s9, v255, 4
	v_readlane_b32 s10, v255, 5
	v_readlane_b32 s11, v255, 6
	v_readlane_b32 s12, v255, 7
	v_readlane_b32 s13, v255, 8
	v_readlane_b32 s14, v255, 9
	v_readlane_b32 s15, v255, 10
	v_readlane_b32 s16, v255, 11
	v_readlane_b32 s17, v255, 12
	v_readlane_b32 s18, v255, 13
	v_readlane_b32 s19, v255, 14
	v_readlane_b32 s20, v255, 15
	v_readlane_b32 s21, v255, 16
	v_readlane_b32 s22, v255, 17
	v_readlane_b32 s23, v255, 18
	s_cbranch_execz .LBB0_106
	v_and_b32_e32 v1, 31, v16
	v_cvt_f32_ubyte0_e32 v1, v1
	v_mul_f32_e32 v2, 0xbed49a78, v1
	s_mov_b32 s1, 0xc2fc0000
	v_mov_b32_e32 v3, 0x42800000
	v_cmp_gt_f32_e32 vcc, s1, v2
	s_mov_b64 s[14:15], s[10:11]
	s_mov_b64 s[12:13], s[8:9]
	v_cndmask_b32_e32 v2, 0, v3, vcc
	v_fmac_f32_e32 v2, 0xbed49a78, v1
	v_exp_f32_e32 v1, v2
	v_not_b32_e32 v2, 63
	v_cndmask_b32_e32 v2, 0, v2, vcc
	s_lshl_b32 s6, s34, 8
	v_ldexp_f32 v4, v1, v2
	v_ashrrev_i32_e32 v1, 31, v0
	v_lshl_add_u64 v[2:3], v[0:1], 2, s[30:31]
	s_mov_b64 s[2:3], 0x4208000
	s_ashr_i32 s7, s6, 31
	s_mov_b32 s12, 0x6dc9c883
	v_lshl_add_u64 v[2:3], v[2:3], 0, s[2:3]
	s_lshl_b64 s[8:9], s[6:7], 2
	s_mov_b64 s[10:11], 0
	s_mov_b32 s13, 0x3fc45f30
	s_mov_b32 s1, 0x3ffff
.LBB0_105:
	s_cmp_lt_u32 s98, 2
	s_cbranch_scc1 .Lrope_pre
	v_ashrrev_i32_e32 v6, 5, v0
	v_ashrrev_i32_e32 v7, 31, v6
	v_lshl_add_u64 v[6:7], v[6:7], 2, s[14:15]
	global_load_dword v1, v[6:7], off
	s_waitcnt vmcnt(0)
	s_branch .Lrope_go
.Lrope_pre:
	v_mov_b32_e32 v1, v252
	s_cmp_eq_u32 s98, 0
	s_cbranch_scc1 .Lrope_go
	v_mov_b32_e32 v1, v253
.Lrope_go:
	s_add_i32 s98, s98, 1
	v_add_co_u32_e32 v6, vcc, 0x100000, v2
	v_add_u32_e32 v0, s6, v0
	s_nop 0
	v_addc_co_u32_e32 v7, vcc, 0, v3, vcc
	v_cmp_lt_i32_e32 vcc, s1, v0
	s_or_b64 s[10:11], vcc, s[10:11]
	v_cvt_f32_i32_e32 v1, v1
	v_mul_f32_e32 v1, v4, v1
	v_cvt_f64_f32_e32 v[8:9], v1
	v_mul_f64 v[10:11], v[8:9], s[12:13]
	v_rndne_f64_e32 v[10:11], v[10:11]
	v_fma_f64 v[8:9], v[8:9], s[12:13], -v[10:11]
	v_cvt_f32_f64_e32 v1, v[8:9]
	v_cos_f32_e32 v5, v1
	v_sin_f32_e32 v1, v1
	global_store_dword v[2:3], v5, off
	global_store_dword v[6:7], v1, off
	v_lshl_add_u64 v[2:3], v[2:3], 0, s[8:9]
	s_andn2_b64 exec, exec, s[10:11]
	s_cbranch_execnz .LBB0_105
